# speedup vs baseline: 1.0039x; 1.0039x over previous
.LBB0_459:
	s_or_saveexec_b64 s[16:17], s[4:5]
	s_nop 0
	v_lshlrev_b32_e32 v128, 2, v157
	v_and_b32_e32 v143, 12, v128
	v_lshlrev_b32_e32 v128, 4, v156
	v_bitop3_b32 v136, v201, 63, v157 bitop3:0xc8
	s_movk_i32 s4, 0xffc0
	v_and_b32_e32 v138, 0xfffffc00, v128
	v_bitop3_b32 v137, v201, s4, v157 bitop3:0xc8
	v_bfe_u32 v139, v156, 2, 4
	v_add_u32_e32 v141, 0x80000, v138
	v_lshlrev_b32_e32 v145, 2, v136
	s_xor_b64 exec, exec, s[16:17]
	s_cbranch_execz .LBB0_463
	v_mov_b32_e32 v128, v246
	s_mov_b32 s4, 0x3f2aaaab
	s_cmp_eq_u32 s45, 0
	s_mov_b32 s18, 0
	s_mov_b32 s19, 56
	v_mul_f32_e32 v128, 0xbfb8aa3b, v128
	v_exp_f32_e32 v130, v128
	s_nop 0
	v_add_f32_e32 v131, 1.0, v130
	v_add_f32_e32 v128, -1.0, v131
	v_sub_f32_e32 v129, v128, v131
	v_add_f32_e32 v129, 1.0, v129
	v_sub_f32_e32 v128, v130, v128
	v_add_f32_e32 v132, v128, v129
	v_frexp_mant_f32_e32 v128, v131
	v_cmp_gt_f32_e64 s[4:5], s4, v128
	v_cvt_f64_f32_e32 v[128:129], v131
	v_frexp_exp_i32_f64_e32 v128, v[128:129]
	v_subbrev_co_u32_e64 v128, s[4:5], 0, v128, s[4:5]
	v_sub_u32_e32 v129, 0, v128
	v_ldexp_f32 v131, v131, v129
	v_ldexp_f32 v129, v132, v129
	v_add_f32_e32 v132, -1.0, v131
	v_add_f32_e32 v133, 1.0, v132
	v_sub_f32_e32 v133, v131, v133
	v_add_f32_e32 v133, v129, v133
	v_add_f32_e32 v134, v132, v133
	v_sub_f32_e32 v132, v134, v132
	v_sub_f32_e32 v132, v133, v132
	v_add_f32_e32 v133, 1.0, v131
	v_add_f32_e32 v135, -1.0, v133
	v_sub_f32_e32 v131, v131, v135
	v_add_f32_e32 v129, v129, v131
	v_add_f32_e32 v131, v133, v129
	v_sub_f32_e32 v133, v131, v133
	v_sub_f32_e32 v129, v129, v133
	v_rcp_f32_e32 v133, v131
	v_cvt_f32_i32_e32 v128, v128
	s_mov_b32 s4, 0x3f317218
	v_mul_f32_e32 v135, v134, v133
	v_mul_f32_e32 v147, v131, v135
	v_fma_f32 v149, v135, v131, -v147
	v_fmac_f32_e32 v149, v135, v129
	v_add_f32_e32 v157, v147, v149
	v_sub_f32_e32 v200, v134, v157
	v_sub_f32_e32 v134, v134, v200
	v_sub_f32_e32 v147, v157, v147
	v_sub_f32_e32 v134, v134, v157
	v_add_f32_e32 v132, v132, v134
	v_sub_f32_e32 v134, v147, v149
	v_add_f32_e32 v132, v134, v132
	v_add_f32_e32 v134, v200, v132
	v_mul_f32_e32 v147, v133, v134
	v_mul_f32_e32 v149, v131, v147
	v_fma_f32 v131, v147, v131, -v149
	v_fmac_f32_e32 v131, v147, v129
	v_sub_f32_e32 v129, v200, v134
	v_add_f32_e32 v129, v132, v129
	v_add_f32_e32 v132, v149, v131
	v_sub_f32_e32 v157, v134, v132
	v_sub_f32_e32 v134, v134, v157
	v_sub_f32_e32 v149, v132, v149
	v_sub_f32_e32 v132, v134, v132
	v_add_f32_e32 v129, v129, v132
	v_sub_f32_e32 v131, v149, v131
	v_add_f32_e32 v129, v131, v129
	v_add_f32_e32 v131, v135, v147
	v_add_f32_e32 v129, v157, v129
	v_sub_f32_e32 v132, v131, v135
	v_mul_f32_e32 v129, v133, v129
	v_sub_f32_e32 v132, v147, v132
	v_add_f32_e32 v129, v132, v129
	v_mul_f32_e32 v135, 0x3f317218, v128
	v_add_f32_e32 v132, v131, v129
	v_fma_f32 v147, v128, s4, -v135
	v_mul_f32_e32 v133, v132, v132
	v_fmac_f32_e32 v147, 0xb102e308, v128
	v_sub_f32_e32 v128, v132, v131
	v_fmamk_f32 v134, v133, 0x3e9b6dac, v185
	v_sub_f32_e32 v128, v129, v128
	v_add_f32_e32 v129, v135, v147
	v_fmaak_f32 v134, v133, v134, 0x3f2aaada
	v_sub_f32_e32 v131, v129, v135
	v_ldexp_f32 v135, v132, 1
	v_mul_f32_e32 v132, v132, v133
	v_mul_f32_e32 v132, v132, v134
	v_add_f32_e32 v133, v135, v132
	v_sub_f32_e32 v134, v133, v135
	v_ldexp_f32 v128, v128, 1
	v_sub_f32_e32 v132, v132, v134
	v_add_f32_e32 v128, v128, v132
	v_add_f32_e32 v132, v133, v128
	v_sub_f32_e32 v133, v132, v133
	v_sub_f32_e32 v128, v128, v133
	v_add_f32_e32 v133, v129, v132
	v_sub_f32_e32 v134, v133, v129
	v_sub_f32_e32 v135, v133, v134
	v_sub_f32_e32 v131, v147, v131
	v_sub_f32_e32 v129, v129, v135
	v_sub_f32_e32 v132, v132, v134
	v_add_f32_e32 v129, v132, v129
	v_add_f32_e32 v132, v131, v128
	v_sub_f32_e32 v134, v132, v131
	v_sub_f32_e32 v135, v132, v134
	v_sub_f32_e32 v131, v131, v135
	v_sub_f32_e32 v128, v128, v134
	v_add_f32_e32 v129, v132, v129
	v_add_f32_e32 v128, v128, v131
	v_add_f32_e32 v131, v133, v129
	v_sub_f32_e32 v132, v131, v133
	v_sub_f32_e32 v129, v129, v132
	v_add_f32_e32 v128, v128, v129
	s_mov_b32 s4, 0x7f800000
	v_add_f32_e32 v128, v131, v128
	v_cmp_neq_f32_e64 s[4:5], s4, v130
	s_nop 1
	v_cndmask_b32_e64 v128, v187, v128, s[4:5]
	v_cmp_ngt_f32_e64 s[4:5], -1.0, v130
	s_nop 1
	v_cndmask_b32_e64 v128, v188, v128, s[4:5]
	v_cmp_neq_f32_e64 s[4:5], -1.0, v130
	s_nop 1
	v_cndmask_b32_e64 v128, v189, v128, s[4:5]
	s_mov_b32 s4, 0x33800000
	v_cmp_lt_f32_e64 s[4:5], |v130|, s4
	s_nop 1
	v_cndmask_b32_e64 v128, v128, v130, s[4:5]
	v_mul_f32_e32 v128, 0xc1000000, v128
	v_mul_f32_e32 v130, 0x3b808081, v128
	v_mov_b32_e32 v128, 0
	s_cselect_b64 s[4:5], -1, 0
	v_mov_b32_e32 v129, v128
	s_cmp_eq_u32 s45, 0
	s_cselect_b32 s34, 0, 0x3ff0
	v_lshlrev_b32_e32 v131, 8, v137
	v_lshl_or_b32 v131, v139, 4, v131
	v_or_b32_e32 v131, v131, v143
	v_or_b32_e32 v131, 0x10000, v131
	v_xor_b32_e32 v131, s34, v131
	s_mov_b32 s34, 0
	v_mul_f32_e32 v132, 0x3fb8aa3b, v130
	v_mov_b32_e32 v134, 0
	v_mov_b32_e32 v252, 0
	v_mov_b32_e32 v253, 0
	v_mov_b32_e32 v254, 0
	v_mov_b32_e32 v255, 0
	v_mov_b32_e32 v248, 0
	v_mov_b32_e32 v249, 0
	v_mov_b32_e32 v250, 0
	v_mov_b32_e32 v251, 0
	ds_read_b32 v226, v131
	v_xor_b32_e32 v243, 0x110, v131
	ds_read_b32 v227, v243
	v_xor_b32_e32 v244, 0x220, v131
	ds_read_b32 v228, v244
	v_xor_b32_e32 v245, 0x330, v131
	ds_read_b32 v229, v245
.Lgscan_q0:
	s_add_i32 s34, s34, 4
	s_lshl_b32 s35, s34, 8
	s_and_b32 s18, s34, 15
	s_lshl_b32 s18, s18, 4
	s_or_b32 s35, s35, s18
	v_xor_b32_e32 v135, s35, v131
	ds_read_b32 v230, v135
	v_xor_b32_e32 v243, 0x110, v135
	ds_read_b32 v231, v243
	v_fma_f32 v129, v252, v129, v248
	v_xor_b32_e32 v244, 0x220, v135
	ds_read_b32 v232, v244
	v_xor_b32_e32 v245, 0x330, v135
	ds_read_b32 v233, v245
	v_fma_f32 v129, v253, v129, v249
	s_waitcnt lgkmcnt(4)
	v_cvt_f32_f16_sdwa v234, v226 dst_sel:DWORD dst_unused:UNUSED_PAD src0_sel:WORD_1
	v_cvt_f32_f16_sdwa v235, v227 dst_sel:DWORD dst_unused:UNUSED_PAD src0_sel:WORD_1
	v_fma_f32 v129, v254, v129, v250
	v_cvt_f32_f16_sdwa v236, v228 dst_sel:DWORD dst_unused:UNUSED_PAD src0_sel:WORD_1
	v_cvt_f32_f16_sdwa v237, v229 dst_sel:DWORD dst_unused:UNUSED_PAD src0_sel:WORD_1
	v_cvt_f32_f16_e32 v226, v226
	v_cvt_f32_f16_e32 v227, v227
	v_fma_f32 v129, v255, v129, v251
	v_cvt_f32_f16_e32 v228, v228
	v_cvt_f32_f16_e32 v229, v229
	v_pk_mul_f32 v[238:239], v[226:227], v[132:133] op_sel_hi:[1,0]
	v_pk_mul_f32 v[240:241], v[228:229], v[132:133] op_sel_hi:[1,0]
	v_pk_add_f32 v[242:243], v[226:227], v[228:229]
	v_exp_f32_e32 v238, v238
	v_exp_f32_e32 v239, v239
	v_exp_f32_e32 v240, v240
	v_exp_f32_e32 v241, v241
	v_add_f32_e32 v242, v242, v243
	v_add_f32_e32 v134, v134, v242
	v_pk_fma_f32 v[242:243], v[238:239], v[238:239], 1.0 op_sel_hi:[1,1,0] neg_lo:[1,0,0] neg_hi:[1,0,0] clamp
	v_pk_fma_f32 v[244:245], v[240:241], v[240:241], 1.0 op_sel_hi:[1,1,0] neg_lo:[1,0,0] neg_hi:[1,0,0] clamp
	v_sqrt_f32_e32 v242, v242
	v_sqrt_f32_e32 v243, v243
	v_sqrt_f32_e32 v244, v244
	v_sqrt_f32_e32 v245, v245
	v_pk_mul_f32 v[234:235], v[242:243], v[234:235]
	v_pk_mul_f32 v[236:237], v[244:245], v[236:237]
	s_add_i32 s34, s34, 4
	s_lshl_b32 s35, s34, 8
	s_and_b32 s18, s34, 15
	s_lshl_b32 s18, s18, 4
	s_or_b32 s35, s35, s18
	v_xor_b32_e32 v135, s35, v131
	ds_read_b32 v226, v135
	v_xor_b32_e32 v243, 0x110, v135
	ds_read_b32 v227, v243
	v_fma_f32 v129, v238, v129, v234
	v_xor_b32_e32 v244, 0x220, v135
	ds_read_b32 v228, v244
	v_xor_b32_e32 v245, 0x330, v135
	ds_read_b32 v229, v245
	v_fma_f32 v129, v239, v129, v235
	s_waitcnt lgkmcnt(4)
	v_cvt_f32_f16_sdwa v248, v230 dst_sel:DWORD dst_unused:UNUSED_PAD src0_sel:WORD_1
	v_cvt_f32_f16_sdwa v249, v231 dst_sel:DWORD dst_unused:UNUSED_PAD src0_sel:WORD_1
	v_fma_f32 v129, v240, v129, v236
	v_cvt_f32_f16_sdwa v250, v232 dst_sel:DWORD dst_unused:UNUSED_PAD src0_sel:WORD_1
	v_cvt_f32_f16_sdwa v251, v233 dst_sel:DWORD dst_unused:UNUSED_PAD src0_sel:WORD_1
	v_cvt_f32_f16_e32 v230, v230
	v_cvt_f32_f16_e32 v231, v231
	v_fma_f32 v129, v241, v129, v237
	v_cvt_f32_f16_e32 v232, v232
	v_cvt_f32_f16_e32 v233, v233
	v_pk_mul_f32 v[252:253], v[230:231], v[132:133] op_sel_hi:[1,0]
	v_pk_mul_f32 v[254:255], v[232:233], v[132:133] op_sel_hi:[1,0]
	v_pk_add_f32 v[242:243], v[230:231], v[232:233]
	v_exp_f32_e32 v252, v252
	v_exp_f32_e32 v253, v253
	v_exp_f32_e32 v254, v254
	v_exp_f32_e32 v255, v255
	v_add_f32_e32 v242, v242, v243
	v_add_f32_e32 v134, v134, v242
	v_pk_fma_f32 v[242:243], v[252:253], v[252:253], 1.0 op_sel_hi:[1,1,0] neg_lo:[1,0,0] neg_hi:[1,0,0] clamp
	v_pk_fma_f32 v[244:245], v[254:255], v[254:255], 1.0 op_sel_hi:[1,1,0] neg_lo:[1,0,0] neg_hi:[1,0,0] clamp
	v_sqrt_f32_e32 v242, v242
	v_sqrt_f32_e32 v243, v243
	v_sqrt_f32_e32 v244, v244
	v_sqrt_f32_e32 v245, v245
	v_pk_mul_f32 v[248:249], v[242:243], v[248:249]
	v_pk_mul_f32 v[250:251], v[244:245], v[250:251]
	s_cmp_lt_u32 s34, 64
	s_cbranch_scc1 .Lgscan_q0
	s_waitcnt lgkmcnt(0)
	v_fma_f32 v129, v252, v129, v248
	v_fma_f32 v129, v253, v129, v249
	v_fma_f32 v129, v254, v129, v250
	v_fma_f32 v129, v255, v129, v251
	v_mul_f32_e32 v128, v130, v134
	v_mul_f32_e32 v128, 0x3fb8aa3b, v128
	v_exp_f32_e32 v128, v128
	v_or_b32_e32 v130, v138, v136
	v_ashrrev_i32_e32 v131, 31, v130
	v_lshl_add_u64 v[130:131], v[130:131], 2, s[14:15]
	global_store_dword v[130:131], v128, off
	v_or_b32_e32 v130, v141, v136
	v_ashrrev_i32_e32 v131, 31, v130
	v_lshl_add_u64 v[130:131], v[130:131], 2, s[14:15]
	v_mov_b32_e32 v200, v156
	global_store_dword v[130:131], v129, off

.LBB0_465:
	s_andn2_saveexec_b64 s[4:5], s[4:5]
	s_cbranch_execz .LBB0_469
	v_mov_b32_e32 v128, v247
	s_mov_b32 s8, 0x3f2aaaab
	s_cmp_eq_u32 s45, 0
	s_mov_b32 s16, 0
	s_mov_b32 s17, 56
	v_mul_f32_e32 v128, 0xbfb8aa3b, v128
	v_exp_f32_e32 v130, v128
	s_nop 0
	v_add_f32_e32 v131, 1.0, v130
	v_add_f32_e32 v128, -1.0, v131
	v_sub_f32_e32 v129, v128, v131
	v_add_f32_e32 v129, 1.0, v129
	v_sub_f32_e32 v128, v130, v128
	v_add_f32_e32 v132, v128, v129
	v_frexp_mant_f32_e32 v128, v131
	v_cmp_gt_f32_e32 vcc, s8, v128
	v_cvt_f64_f32_e32 v[128:129], v131
	v_frexp_exp_i32_f64_e32 v128, v[128:129]
	v_subbrev_co_u32_e32 v128, vcc, 0, v128, vcc
	v_sub_u32_e32 v129, 0, v128
	v_ldexp_f32 v131, v131, v129
	v_ldexp_f32 v129, v132, v129
	v_add_f32_e32 v132, -1.0, v131
	v_add_f32_e32 v133, 1.0, v132
	v_sub_f32_e32 v133, v131, v133
	v_add_f32_e32 v133, v129, v133
	v_add_f32_e32 v134, v132, v133
	v_sub_f32_e32 v132, v134, v132
	v_sub_f32_e32 v132, v133, v132
	v_add_f32_e32 v133, 1.0, v131
	v_add_f32_e32 v135, -1.0, v133
	v_sub_f32_e32 v131, v131, v135
	v_add_f32_e32 v129, v129, v131
	v_add_f32_e32 v131, v133, v129
	v_sub_f32_e32 v133, v131, v133
	v_sub_f32_e32 v129, v129, v133
	v_rcp_f32_e32 v133, v131
	v_cvt_f32_i32_e32 v128, v128
	s_mov_b32 s8, 0x3f317218
	v_mul_f32_e32 v135, v134, v133
	v_mul_f32_e32 v140, v131, v135
	v_fma_f32 v142, v135, v131, -v140
	v_fmac_f32_e32 v142, v135, v129
	v_add_f32_e32 v144, v140, v142
	v_sub_f32_e32 v145, v134, v144
	v_sub_f32_e32 v134, v134, v145
	v_sub_f32_e32 v140, v144, v140
	v_sub_f32_e32 v134, v134, v144
	v_add_f32_e32 v132, v132, v134
	v_sub_f32_e32 v134, v140, v142
	v_add_f32_e32 v132, v134, v132
	v_add_f32_e32 v134, v145, v132
	v_mul_f32_e32 v140, v133, v134
	v_mul_f32_e32 v142, v131, v140
	v_fma_f32 v131, v140, v131, -v142
	v_fmac_f32_e32 v131, v140, v129
	v_sub_f32_e32 v129, v145, v134
	v_add_f32_e32 v129, v132, v129
	v_add_f32_e32 v132, v142, v131
	v_sub_f32_e32 v144, v134, v132
	v_sub_f32_e32 v134, v134, v144
	v_sub_f32_e32 v142, v132, v142
	v_sub_f32_e32 v132, v134, v132
	v_add_f32_e32 v129, v129, v132
	v_sub_f32_e32 v131, v142, v131
	v_add_f32_e32 v129, v131, v129
	v_add_f32_e32 v131, v135, v140
	v_add_f32_e32 v129, v144, v129
	v_sub_f32_e32 v132, v131, v135
	v_mul_f32_e32 v129, v133, v129
	v_sub_f32_e32 v132, v140, v132
	v_add_f32_e32 v129, v132, v129
	v_mul_f32_e32 v135, 0x3f317218, v128
	v_add_f32_e32 v132, v131, v129
	v_fma_f32 v140, v128, s8, -v135
	v_mul_f32_e32 v133, v132, v132
	v_fmac_f32_e32 v140, 0xb102e308, v128
	v_sub_f32_e32 v128, v132, v131
	v_fmamk_f32 v134, v133, 0x3e9b6dac, v185
	v_sub_f32_e32 v128, v129, v128
	v_add_f32_e32 v129, v135, v140
	v_fmaak_f32 v134, v133, v134, 0x3f2aaada
	v_sub_f32_e32 v131, v129, v135
	v_ldexp_f32 v135, v132, 1
	v_mul_f32_e32 v132, v132, v133
	v_mul_f32_e32 v132, v132, v134
	v_add_f32_e32 v133, v135, v132
	v_sub_f32_e32 v134, v133, v135
	v_ldexp_f32 v128, v128, 1
	v_sub_f32_e32 v132, v132, v134
	v_add_f32_e32 v128, v128, v132
	v_add_f32_e32 v132, v133, v128
	v_sub_f32_e32 v133, v132, v133
	v_sub_f32_e32 v128, v128, v133
	v_add_f32_e32 v133, v129, v132
	v_sub_f32_e32 v134, v133, v129
	v_sub_f32_e32 v135, v133, v134
	v_sub_f32_e32 v131, v140, v131
	v_sub_f32_e32 v129, v129, v135
	v_sub_f32_e32 v132, v132, v134
	v_add_f32_e32 v129, v132, v129
	v_add_f32_e32 v132, v131, v128
	v_sub_f32_e32 v134, v132, v131
	v_sub_f32_e32 v135, v132, v134
	v_sub_f32_e32 v131, v131, v135
	v_sub_f32_e32 v128, v128, v134
	v_add_f32_e32 v129, v132, v129
	v_add_f32_e32 v128, v128, v131
	v_add_f32_e32 v131, v133, v129
	v_sub_f32_e32 v132, v131, v133
	v_sub_f32_e32 v129, v129, v132
	v_add_f32_e32 v128, v128, v129
	s_mov_b32 s8, 0x7f800000
	v_add_f32_e32 v128, v131, v128
	v_cmp_neq_f32_e32 vcc, s8, v130
	s_mov_b32 s8, 0x33800000
	s_nop 0
	v_cndmask_b32_e32 v128, v187, v128, vcc
	v_cmp_ngt_f32_e32 vcc, -1.0, v130
	s_nop 1
	v_cndmask_b32_e32 v128, v188, v128, vcc
	v_cmp_neq_f32_e32 vcc, -1.0, v130
	s_nop 1
	v_cndmask_b32_e32 v128, v189, v128, vcc
	v_cmp_lt_f32_e64 vcc, |v130|, s8
	s_cselect_b64 s[8:9], -1, 0
	s_nop 0
	v_cndmask_b32_e32 v128, v128, v130, vcc
	v_mul_f32_e32 v128, 0xc1000000, v128
	v_mul_f32_e32 v130, 0x3b808081, v128
	v_mov_b32_e32 v128, 0
	v_mov_b32_e32 v129, v128
	s_cmp_eq_u32 s45, 0
	s_cselect_b32 s34, 0, 0x3ff0
	v_lshlrev_b32_e32 v131, 8, v137
	v_lshl_or_b32 v131, v139, 4, v131
	v_or_b32_e32 v131, v131, v143
	v_or_b32_e32 v131, 0x10000, v131
	v_xor_b32_e32 v131, s34, v131
	s_mov_b32 s34, 0
	v_mul_f32_e32 v132, 0x3fb8aa3b, v130
	v_mov_b32_e32 v134, 0
	v_mov_b32_e32 v252, 0
	v_mov_b32_e32 v253, 0
	v_mov_b32_e32 v254, 0
	v_mov_b32_e32 v255, 0
	v_mov_b32_e32 v248, 0
	v_mov_b32_e32 v249, 0
	v_mov_b32_e32 v250, 0
	v_mov_b32_e32 v251, 0
	ds_read_b32 v226, v131
	v_xor_b32_e32 v243, 0x110, v131
	ds_read_b32 v227, v243
	v_xor_b32_e32 v244, 0x220, v131
	ds_read_b32 v228, v244
	v_xor_b32_e32 v245, 0x330, v131
	ds_read_b32 v229, v245
.Lgscan_q1:
	s_add_i32 s34, s34, 4
	s_lshl_b32 s35, s34, 8
	s_and_b32 s18, s34, 15
	s_lshl_b32 s18, s18, 4
	s_or_b32 s35, s35, s18
	v_xor_b32_e32 v135, s35, v131
	ds_read_b32 v230, v135
	v_xor_b32_e32 v243, 0x110, v135
	ds_read_b32 v231, v243
	v_fma_f32 v129, v252, v129, v248
	v_xor_b32_e32 v244, 0x220, v135
	ds_read_b32 v232, v244
	v_xor_b32_e32 v245, 0x330, v135
	ds_read_b32 v233, v245
	v_fma_f32 v129, v253, v129, v249
	s_waitcnt lgkmcnt(4)
	v_cvt_f32_f16_sdwa v234, v226 dst_sel:DWORD dst_unused:UNUSED_PAD src0_sel:WORD_1
	v_cvt_f32_f16_sdwa v235, v227 dst_sel:DWORD dst_unused:UNUSED_PAD src0_sel:WORD_1
	v_fma_f32 v129, v254, v129, v250
	v_cvt_f32_f16_sdwa v236, v228 dst_sel:DWORD dst_unused:UNUSED_PAD src0_sel:WORD_1
	v_cvt_f32_f16_sdwa v237, v229 dst_sel:DWORD dst_unused:UNUSED_PAD src0_sel:WORD_1
	v_cvt_f32_f16_e32 v226, v226
	v_cvt_f32_f16_e32 v227, v227
	v_fma_f32 v129, v255, v129, v251
	v_cvt_f32_f16_e32 v228, v228
	v_cvt_f32_f16_e32 v229, v229
	v_pk_mul_f32 v[238:239], v[226:227], v[132:133] op_sel_hi:[1,0]
	v_pk_mul_f32 v[240:241], v[228:229], v[132:133] op_sel_hi:[1,0]
	v_pk_add_f32 v[242:243], v[226:227], v[228:229]
	v_exp_f32_e32 v238, v238
	v_exp_f32_e32 v239, v239
	v_exp_f32_e32 v240, v240
	v_exp_f32_e32 v241, v241
	v_add_f32_e32 v242, v242, v243
	v_add_f32_e32 v134, v134, v242
	v_pk_fma_f32 v[242:243], v[238:239], v[238:239], 1.0 op_sel_hi:[1,1,0] neg_lo:[1,0,0] neg_hi:[1,0,0] clamp
	v_pk_fma_f32 v[244:245], v[240:241], v[240:241], 1.0 op_sel_hi:[1,1,0] neg_lo:[1,0,0] neg_hi:[1,0,0] clamp
	v_sqrt_f32_e32 v242, v242
	v_sqrt_f32_e32 v243, v243
	v_sqrt_f32_e32 v244, v244
	v_sqrt_f32_e32 v245, v245
	v_pk_mul_f32 v[234:235], v[242:243], v[234:235]
	v_pk_mul_f32 v[236:237], v[244:245], v[236:237]
	s_add_i32 s34, s34, 4
	s_lshl_b32 s35, s34, 8
	s_and_b32 s18, s34, 15
	s_lshl_b32 s18, s18, 4
	s_or_b32 s35, s35, s18
	v_xor_b32_e32 v135, s35, v131
	ds_read_b32 v226, v135
	v_xor_b32_e32 v243, 0x110, v135
	ds_read_b32 v227, v243
	v_fma_f32 v129, v238, v129, v234
	v_xor_b32_e32 v244, 0x220, v135
	ds_read_b32 v228, v244
	v_xor_b32_e32 v245, 0x330, v135
	ds_read_b32 v229, v245
	v_fma_f32 v129, v239, v129, v235
	s_waitcnt lgkmcnt(4)
	v_cvt_f32_f16_sdwa v248, v230 dst_sel:DWORD dst_unused:UNUSED_PAD src0_sel:WORD_1
	v_cvt_f32_f16_sdwa v249, v231 dst_sel:DWORD dst_unused:UNUSED_PAD src0_sel:WORD_1
	v_fma_f32 v129, v240, v129, v236
	v_cvt_f32_f16_sdwa v250, v232 dst_sel:DWORD dst_unused:UNUSED_PAD src0_sel:WORD_1
	v_cvt_f32_f16_sdwa v251, v233 dst_sel:DWORD dst_unused:UNUSED_PAD src0_sel:WORD_1
	v_cvt_f32_f16_e32 v230, v230
	v_cvt_f32_f16_e32 v231, v231
	v_fma_f32 v129, v241, v129, v237
	v_cvt_f32_f16_e32 v232, v232
	v_cvt_f32_f16_e32 v233, v233
	v_pk_mul_f32 v[252:253], v[230:231], v[132:133] op_sel_hi:[1,0]
	v_pk_mul_f32 v[254:255], v[232:233], v[132:133] op_sel_hi:[1,0]
	v_pk_add_f32 v[242:243], v[230:231], v[232:233]
	v_exp_f32_e32 v252, v252
	v_exp_f32_e32 v253, v253
	v_exp_f32_e32 v254, v254
	v_exp_f32_e32 v255, v255
	v_add_f32_e32 v242, v242, v243
	v_add_f32_e32 v134, v134, v242
	v_pk_fma_f32 v[242:243], v[252:253], v[252:253], 1.0 op_sel_hi:[1,1,0] neg_lo:[1,0,0] neg_hi:[1,0,0] clamp
	v_pk_fma_f32 v[244:245], v[254:255], v[254:255], 1.0 op_sel_hi:[1,1,0] neg_lo:[1,0,0] neg_hi:[1,0,0] clamp
	v_sqrt_f32_e32 v242, v242
	v_sqrt_f32_e32 v243, v243
	v_sqrt_f32_e32 v244, v244
	v_sqrt_f32_e32 v245, v245
	v_pk_mul_f32 v[248:249], v[242:243], v[248:249]
	v_pk_mul_f32 v[250:251], v[244:245], v[250:251]
	s_cmp_lt_u32 s34, 64
	s_cbranch_scc1 .Lgscan_q1
	s_waitcnt lgkmcnt(0)
	v_fma_f32 v129, v252, v129, v248
	v_fma_f32 v129, v253, v129, v249
	v_fma_f32 v129, v254, v129, v250
	v_fma_f32 v129, v255, v129, v251
	v_mul_f32_e32 v128, v130, v134
	v_mul_f32_e32 v128, 0x3fb8aa3b, v128
	v_exp_f32_e32 v128, v128
	v_ashrrev_i32_e32 v139, 31, v138
	v_mov_b32_e32 v137, v164
	v_lshl_add_u64 v[130:131], v[136:137], 0, v[138:139]
	v_lshl_add_u64 v[130:131], v[130:131], 2, s[14:15]
	global_store_dword v[130:131], v128, off offset:256
	v_or3_b32 v130, v136, v141, 64
	v_ashrrev_i32_e32 v131, 31, v130
	v_lshl_add_u64 v[130:131], v[130:131], 2, s[14:15]
	global_store_dword v[130:131], v129, off

; __global__ void __launch_bounds__(512) fwd_megakernel(Params p_unused) {
	.amdhsa_kernel _Z14fwd_megakernel6Params
		.amdhsa_group_segment_fixed_size 139264
		.amdhsa_private_segment_fixed_size 0
		.amdhsa_kernarg_size 456
		.amdhsa_user_sgpr_count 2
		.amdhsa_user_sgpr_dispatch_ptr 0
		.amdhsa_user_sgpr_queue_ptr 0
		.amdhsa_user_sgpr_kernarg_segment_ptr 1
		.amdhsa_user_sgpr_dispatch_id 0
		.amdhsa_user_sgpr_kernarg_preload_length 0
		.amdhsa_user_sgpr_kernarg_preload_offset 0
		.amdhsa_user_sgpr_private_segment_size 0
		.amdhsa_uses_dynamic_stack 0
		.amdhsa_enable_private_segment 0
		.amdhsa_system_sgpr_workgroup_id_x 1
		.amdhsa_system_sgpr_workgroup_id_y 0
		.amdhsa_system_sgpr_workgroup_id_z 0
		.amdhsa_system_sgpr_workgroup_info 0
		.amdhsa_system_vgpr_workitem_id 2
		.amdhsa_next_free_vgpr 256
		.amdhsa_next_free_sgpr 100
		.amdhsa_accum_offset 256
		.amdhsa_reserve_vcc 1
		.amdhsa_float_round_mode_32 0
		.amdhsa_float_round_mode_16_64 0
		.amdhsa_float_denorm_mode_32 3
		.amdhsa_float_denorm_mode_16_64 3
		.amdhsa_dx10_clamp 1
		.amdhsa_ieee_mode 1
		.amdhsa_fp16_overflow 0
		.amdhsa_tg_split 0
		.amdhsa_exception_fp_ieee_invalid_op 0
		.amdhsa_exception_fp_denorm_src 0
		.amdhsa_exception_fp_ieee_div_zero 0
		.amdhsa_exception_fp_ieee_overflow 0
		.amdhsa_exception_fp_ieee_underflow 0
		.amdhsa_exception_fp_ieee_inexact 0
		.amdhsa_exception_int_div_zero 0
	.end_amdhsa_kernel

; __global__ void __launch_bounds__(512) fwd_megakernel(Params p_unused) {
amdhsa.kernels:
  - .agpr_count:     0
    .args:
      - .offset:         0
        .size:           200
        .value_kind:     by_value
      - .offset:         200
        .size:           4
        .value_kind:     hidden_block_count_x
      - .offset:         204
        .size:           4
        .value_kind:     hidden_block_count_y
      - .offset:         208
        .size:           4
        .value_kind:     hidden_block_count_z
      - .offset:         212
        .size:           2
        .value_kind:     hidden_group_size_x
      - .offset:         214
        .size:           2
        .value_kind:     hidden_group_size_y
      - .offset:         216
        .size:           2
        .value_kind:     hidden_group_size_z
      - .offset:         218
        .size:           2
        .value_kind:     hidden_remainder_x
      - .offset:         220
        .size:           2
        .value_kind:     hidden_remainder_y
      - .offset:         222
        .size:           2
        .value_kind:     hidden_remainder_z
      - .offset:         240
        .size:           8
        .value_kind:     hidden_global_offset_x
      - .offset:         248
        .size:           8
        .value_kind:     hidden_global_offset_y
      - .offset:         256
        .size:           8
        .value_kind:     hidden_global_offset_z
      - .offset:         264
        .size:           2
        .value_kind:     hidden_grid_dims
      - .offset:         288
        .size:           8
        .value_kind:     hidden_multigrid_sync_arg
    .group_segment_fixed_size: 139264
    .kernarg_segment_align: 8
    .kernarg_segment_size: 456
    .language:       OpenCL C
    .language_version:
      - 2
      - 0
    .max_flat_workgroup_size: 512
    .name:           _Z14fwd_megakernel6Params
    .private_segment_fixed_size: 0
    .sgpr_count:     106
    .sgpr_spill_count: 125
    .symbol:         _Z14fwd_megakernel6Params.kd
    .uniform_work_group_size: 1
    .uses_dynamic_stack: false
    .vgpr_count:     256
    .vgpr_spill_count: 0
    .wavefront_size: 64
